# baseline (speedup 1.0000x reference)
; template <bool MLA>
; __device__ __forceinline__ void attn_meta_item(unsigned char* smem, const Params& p, int b, int hh, int quarter, int aslot) {
;     constexpr int NS = MLA ? 12 : 4;
;     float* ored = (float*)smem;
;     float* mred = ored + 8 * 128 * 32;
;     float* lred = mred + 8 * 32;
;     const int tid = otid(), lane = tid & 63, w = tid >> 6, l31 = lane & 31, h5 = lane >> 5;
;     const int qpos = l31 & 15;
;     const size_t qrow = (size_t)b * L + qpos;
;     const bf16_t* qbase;
;     bf16_t* obase;
;     const bf16_t* k1; const bf16_t* k2 = nullptr; const bf16_t* vt;
;     if constexpr (MLA) {
;         bf16_t* qb = (bf16_t*)(p.ws + OFF_Q);
;         qbase = qb + qrow * 3072 + hh * 192;
;         obase = qb + (size_t)b * L * 3072 + hh * 192;
;         k1 = (const bf16_t*)(p.ws + OFF_KNOPE) + (size_t)b * L * 2048 + hh * 128;
;         k2 = (const bf16_t*)(p.ws + OFF_KROPE) + (size_t)b * L * 64;
;         vt = (const bf16_t*)(p.ws + OFF_VT) + (size_t)(b * 16 + hh) * 128 * LP;
;     } else {
;         const bf16_t* qk = (const bf16_t*)(p.ws + OFF_DQK);
;         qbase = qk + qrow * 2048 + (hh >> 1) * 128 + (hh & 1) * 64;
;         obase = (bf16_t*)(p.ws + OFF_DOM) + (size_t)b * L * 2048 + hh * 128;
;         k1 = qk + (size_t)b * L * 2048 + 1024 + (hh >> 1) * 128 + (hh & 1) * 64;
;         vt = (const bf16_t*)(p.ws + OFF_DVT) + (size_t)(b * 8 + (hh >> 1)) * 128 * LP;
;     }
;     bf16x8 qf[NS];
;     attn_load_q<MLA>(p, qbase, qpos, h5, qf);
;     const float c1 = (MLA ? 0.07216878364870322f : 0.125f) * LOG2E;
;     float slope2 = 0.f;
;     if constexpr (!MLA) slope2 = exp2f(-(float)((hh >> 1) + 1)) * LOG2E;
;     f32x16 o[4];
; #pragma unroll
; template <bool MLA>
; __device__ __forceinline__ void attn_phase(unsigned char* smem, const Params& p, int aslot) {
;     ...
;     for (int r = 0; r * (int)gridDim.x < total; ++r) {
;         const int u = work_index(r);
;         if (u >= total) continue;
;         if (u < nmain) {
;             const int bh = u / NQT, qt = u - bh * NQT;
;             const int bb = bh / NH;
;             int hx = bh % NH;
;             if constexpr (!MLA) hx ^= ((0x7430 >> (4 * bb)) & 7) << 1;
;             attn_item<MLA>(smem, p, bb, hx, qt);
;         } else {
;             const int mi = u - nmain, bh = mi >> 2;
;             attn_meta_item<MLA>(smem, p, bh / NH, bh % NH, mi & 3, aslot);
.LBB0_1269:
.LBB0_1270:
.LBB0_1271:
	s_cmp_eq_u32 s10, 1
	s_cbranch_scc1 .LBB0_1336
	v_readfirstlane_b32 s0, v166
	s_cmp_lt_u32 s0, 64
	s_cbranch_scc0 .Ldq_wait
	s_mov_b64 s[2:3], exec
	s_mov_b64 exec, 1
	v_mov_b32_e32 v2, 0x5000
	v_mov_b32_e32 v3, 1
	s_nop 0
	global_atomic_add v3, v2, v3, s[58:59] sc0
	v_mov_b32_e32 v2, 0x23f00
	s_waitcnt vmcnt(0)
	ds_write_b32 v2, v3
	s_waitcnt lgkmcnt(0)
	s_mov_b64 exec, s[2:3]
.Ldq_wait:
	s_barrier
	v_mov_b32_e32 v2, 0x23f00
	ds_read_b32 v3, v2
	s_waitcnt lgkmcnt(0)
	v_readfirstlane_b32 s0, v3
	s_cmpk_gt_i32 s0, 0x3ff
	s_cbranch_scc0 .Ldq_main
	s_mov_b32 s10, 1
	s_or_b32 s0, s96, 32
	s_mul_i32 s12, s0, s41
	s_add_i32 s12, s12, s26
	s_branch .Ldq_mapped
.Ldq_main:
	s_lshr_b32 s1, s0, 7
	s_sub_i32 s1, 7, s1
	s_bfe_u32 s2, s0, 0x10004
	s_lshl_b32 s1, s1, 1
	s_or_b32 s1, s1, s2
	s_bfe_u32 s2, s0, 0x20005
	s_lshl_b32 s3, s2, 2
	s_lshr_b32 s3, 0xe860, s3
	s_and_b32 s3, s3, 14
	s_xor_b32 s1, s1, s3
	s_lshl_b32 s1, s1, 4
	s_lshl_b32 s2, s2, 8
	s_and_b32 s3, s0, 15
	s_or_b32 s12, s1, s2
	s_or_b32 s12, s12, s3
.Ldq_mapped:
	s_lshl_b32 s11, s12, 8
	s_cmpk_gt_i32 s12, 0x4ff
	s_cbranch_scc1 .LBB0_1270
	s_cmpk_gt_i32 s12, 0x3ff
	s_mov_b64 s[0:1], -1
	s_cbranch_scc0 .LBB0_1294
	s_add_i32 s0, s12, 0xfffffc00
	s_lshr_b32 s8, s0, 6
	v_mov_b32_e32 v114, v166
	s_mul_i32 s0, s8, 0x1010
	v_and_b32_e32 v128, 15, v114
	s_lshr_b32 s1, s12, 2
	v_or_b32_e32 v0, s0, v128
	v_lshlrev_b32_e32 v0, 12, v0
	s_bfe_u32 s4, s1, 0x30001
	v_readlane_b32 s14, v251, 18
	v_lshl_add_u64 v[2:3], s[30:31], 0, v[0:1]
	v_readlane_b32 s15, v251, 19
	s_lshl_b32 s14, s4, 8
	s_lshl_b32 s0, s12, 5
	v_bfe_u32 v115, v114, 5, 1
	v_lshl_add_u64 v[2:3], v[2:3], 0, s[14:15]
	s_and_b32 s0, s0, 0x80
	s_mov_b32 s1, s15
	v_lshl_add_u64 v[2:3], v[2:3], 0, s[0:1]
	v_lshlrev_b32_e32 v0, 4, v115
	v_lshl_add_u64 v[2:3], v[2:3], 0, v[0:1]
	global_load_dwordx4 v[98:101], v[2:3], off
	global_load_dwordx4 v[102:105], v[2:3], off offset:32
	global_load_dwordx4 v[106:109], v[2:3], off offset:64
	global_load_dwordx4 v[110:113], v[2:3], off offset:96
	s_mul_i32 s2, s8, 0x808000
	s_mov_b32 s3, s15
	s_bfe_u32 s13, s12, 0x40002
	s_lshl_b32 s5, s4, 7
	s_lshl_b64 s[2:3], s[2:3], 1
	s_add_u32 s1, s30, s2
	s_addc_u32 s6, s31, s3
	s_add_u32 s1, s1, s14
	s_addc_u32 s6, s6, 0
	s_add_u32 s0, s1, s0
	s_addc_u32 s1, s6, 0
	s_add_i32 s4, s4, 1
	v_cvt_f32_ubyte0_e32 v3, s4
	s_mov_b32 s4, 0x42fc0000
	v_cmp_lt_f32_e32 vcc, s4, v3
	s_lshl_b32 s6, s8, 10
	s_or_b32 s5, s5, s6
	v_cndmask_b32_e32 v4, 0, v182, vcc
	v_sub_f32_e32 v3, v4, v3
	v_exp_f32_e32 v3, v3
	s_mul_i32 s14, s5, 0x1040
	s_and_b64 s[4:5], vcc, exec
	s_cselect_b32 s4, 0xffffffc0, 0
	v_ldexp_f32 v3, v3, s4
	s_lshl_b64 s[4:5], s[14:15], 1
	v_readlane_b32 s6, v252, 59
	v_readlane_b32 s7, v252, 60
	s_add_u32 s4, s6, s4
	v_ashrrev_i32_e32 v129, 6, v114
	s_addc_u32 s5, s7, s5
	v_mul_f32_e32 v117, 0x3fb8aa3b, v3
	v_readlane_b32 s6, v253, 39
	v_and_b32_e32 v3, 64, v183
	v_cmp_eq_u32_e32 vcc, 7, v129
	v_readlane_b32 s7, v253, 40
	v_lshl_add_u64 v[118:119], s[0:1], 0, v[0:1]
	v_xor_b32_e32 v0, 32, v183
	v_add_u32_e32 v3, 64, v3
	s_and_b64 s[6:7], s[6:7], vcc
	v_cmp_lt_i32_e32 vcc, v0, v3
	v_and_b32_e32 v130, 31, v114
	v_lshlrev_b32_e32 v2, 3, v115
	v_cndmask_b32_e32 v0, v183, v0, vcc
	v_lshlrev_b32_e32 v134, 2, v0
	v_mul_u32_u24_e32 v0, 0x1040, v130
	v_lshlrev_b32_e32 v0, 1, v0
	v_mov_b32_e32 v34, v1
	v_mov_b32_e32 v35, v1
	v_mov_b32_e32 v48, v1
	v_mov_b32_e32 v49, v1
	v_lshl_add_u64 v[120:121], s[4:5], 0, v[0:1]
	v_readlane_b32 s0, v253, 41
	v_mov_b32_e32 v36, v1
	v_mov_b32_e32 v37, v1
	v_mov_b32_e32 v38, v1
	v_mov_b32_e32 v39, v1
	v_mov_b32_e32 v40, v1
	v_mov_b32_e32 v41, v1
	v_mov_b32_e32 v42, v1
	v_mov_b32_e32 v43, v1
	v_mov_b32_e32 v44, v1
	v_mov_b32_e32 v45, v1
	v_mov_b32_e32 v46, v1
	v_mov_b32_e32 v47, v1
	v_lshlrev_b32_e32 v0, 1, v2
	v_mov_b64_e32 v[64:65], v[48:49]
	v_mov_b64_e32 v[18:19], v[34:35]
	v_mov_b64_e32 v[2:3], v[34:35]
	s_mov_b32 s9, 0
	s_mov_b32 s21, s15
	v_cndmask_b32_e64 v132, 4, 5, s[6:7]
	v_lshlrev_b32_e32 v133, 2, v115
	v_lshl_add_u32 v135, v129, 2, s0
	v_mov_b32_e32 v136, 0xff800000
	v_mov_b32_e32 v131, 0
	s_mov_b64 s[4:5], 0
	v_mov_b64_e32 v[62:63], v[46:47]
	v_mov_b64_e32 v[60:61], v[44:45]
	v_mov_b64_e32 v[58:59], v[42:43]
	v_mov_b64_e32 v[56:57], v[40:41]
	v_mov_b64_e32 v[54:55], v[38:39]
	v_mov_b64_e32 v[52:53], v[36:37]
	v_mov_b64_e32 v[50:51], v[34:35]
	v_mov_b64_e32 v[20:21], v[36:37]
	v_mov_b64_e32 v[22:23], v[38:39]
	v_mov_b64_e32 v[24:25], v[40:41]
	v_mov_b64_e32 v[26:27], v[42:43]
	v_mov_b64_e32 v[28:29], v[44:45]
	v_mov_b64_e32 v[30:31], v[46:47]
	v_mov_b64_e32 v[32:33], v[48:49]
	v_mov_b64_e32 v[4:5], v[36:37]
	v_mov_b64_e32 v[6:7], v[38:39]
	v_mov_b64_e32 v[8:9], v[40:41]
	v_mov_b64_e32 v[10:11], v[42:43]
	v_mov_b64_e32 v[12:13], v[44:45]
	v_mov_b64_e32 v[14:15], v[46:47]
	v_mov_b64_e32 v[16:17], v[48:49]
	s_branch .LBB0_1275
